# attention: 4 more Q fragments kept resident in VGPRs for the whole key loop (4 of 32 ds_read_b128 per step removed)
# speedup vs baseline: 1.0112x; 1.0112x over previous
; #define LAS __attribute__((address_space(3)))
; #define SBAR() __builtin_amdgcn_sched_barrier(0)
; #define DMA_K(t, bf) do { if (ABL & 8) break; const char* kb_ = Kt + (size_t)(t) * KSTEP; LAS unsigned char* kd_ = Kl + (bf) * SHM_K + wid * 1024; \
;     glds16(kb_ + voffK, kd_); glds16(kb_ + 128 + voffK, kd_ + 8192); glds16(Pt + (size_t)(t) * PSTEP + voffP, kd_ + 16384); } while (0)
; #define DMA_V(t, bf) do { if (ABL & 8) break; const char* vb_ = Kt + 256 + (size_t)(t) * KSTEP; LAS unsigned char* vd_ = Vl + (bf) * SHM_V + wid * 1024; \
;     glds16(vb_ + voffV, vd_); glds16(vb_ + (size_t)32 * LDKV * 2 + voffV, vd_ + 8192); } while (0)
; #define END_STEP() do { if (!(ABL & 8)) { asm volatile("s_waitcnt vmcnt(0)" ::: "memory"); __syncthreads(); } } while (0)
; #define RESC(a) do { if (__any((a) < 1.f)) { if (hi == 0) al_l[r32] = (a); asm volatile("s_waitcnt lgkmcnt(0)" ::: "memory"); \
;     _Pragma("unroll") for (int d = 0; d < 4; ++d) _Pragma("unroll") for (int r = 0; r < 16; ++r) o[d][r] *= al_l[crow(r, hi)]; } } while (0)
; #define PV_TILE(VB, C0, C1, alC, PAR) do { s16x4 va_[8], vb_[8]; float ma_ = 0.f, mb_ = 0.f, mn_ = 0.f; VRD8(VB, 0, va_); SBAR(); \
;     PV_BLK(VB, 0, va_, vb_, C0, C1, PAR); if (PAR) { DECIDE(alC); } SBAR(); \
;     PV_BLK(VB, 1, vb_, va_, C0, C1, PAR); PV_BLK(VB, 2, va_, vb_, C0, C1, PAR); PV_BLK(VB, 3, vb_, va_, C0, C1, PAR); } while (0)
; template <int ABL> __device__ __forceinline__ void attn_unit(int b, int h, int qb, const bf16_t* Q, const bf16_t* KV, const bf16_t* KPE, bf16_t* MG, float* ssqa, LAS unsigned char* L) {
;     ...
;   for (int d0 = 0; d0 < 4; ++d0) qr[d0] = ld8(Qw + d0 * 16);
; #pragma unroll
;   for (int dd = 0; dd < 8; ++dd) *reinterpret_cast<LAS bf16x8*>(Qr + (dd >> 2) * 4096 + kro + (((2 * (dd & 3) + hi) ^ ksw) << 4)) = ld8(Qw + (4 + dd) * 16);
;     ...
;   END_STEP();
;   QK_TILE(Kl, pA0, pA1, pA0, pA1, 1.f, false); PAR_ONLY(pA0, pA1, alA);
;   RESC(alA);
;   END_STEP(); DMA_K(2, 0); DMA_V(1, 1);
;   for (int j = 1; j + 1 < NT; j += 2) {
;     SBAR(); QK_TILE(Kl + SHM_K, pB0, pB1, pA0, pA1, alA, true);
;     SBAR(); PAR_ONLY(pB0, pB1, alB); SBAR(); PV_TILE(Vp, pB0, pB1, alB, false);
;     RESC(alB);
;     END_STEP(); DMA_K(j + 2, 1); DMA_V(j + 1, 0);
.LBB0_753:
	s_mov_b32 m0, s59
	v_sub_f32_e32 v1, v36, v140
	v_sub_f32_e32 v2, v37, v140
	v_lshl_add_u64 v[36:37], v[52:53], 0, s[8:9]
	s_mov_b64 s[0:1], 0x80080
	s_waitcnt vmcnt(0)
	s_barrier
	global_load_lds_dwordx4 v[36:37], off
	v_lshl_add_u64 v[36:37], v[52:53], 0, s[0:1]
	s_mov_b32 m0, s60
	s_mov_b64 s[0:1], 0x40100
	global_load_lds_dwordx4 v[36:37], off
	v_lshl_add_u64 v[36:37], v[54:55], 0, s[10:11]
	s_mov_b32 m0, s61
	s_add_i32 s79, s58, 0x4000
	global_load_lds_dwordx4 v[36:37], off
	v_lshl_add_u64 v[36:37], v[142:143], 0, s[0:1]
	s_mov_b32 m0, s79
	s_mov_b64 s[0:1], 0x60100
	s_add_i32 s80, s58, 0x6000
	global_load_lds_dwordx4 v[36:37], off
	v_lshl_add_u64 v[36:37], v[142:143], 0, s[0:1]
	s_mov_b32 m0, s80
	v_exp_f32_e32 v68, v1
	global_load_lds_dwordx4 v[36:37], off
	v_exp_f32_e32 v1, v2
	v_lshlrev_b32_e32 v2, 3, v56
	v_sub_f32_e32 v130, v20, v140
	v_sub_f32_e32 v131, v21, v140
	v_sub_f32_e32 v132, v22, v140
	v_and_b32_e32 v20, 24, v2
	v_and_b32_e32 v21, 0xc0, v62
	v_lshlrev_b32_e32 v22, 1, v56
	s_lshr_b32 s54, s2, 4
	v_and_b32_e32 v22, 32, v22
	v_and_b32_e32 v2, 0x100, v2
	v_add3_u32 v20, 0, v20, v21
	s_and_b32 s0, s54, 7
	v_add3_u32 v167, v20, v22, v2
	v_lshlrev_b32_e32 v2, 7, v57
	s_lshl_b32 s54, s0, 9
	s_add_i32 s0, 0, 0x10000
	v_add3_u32 v2, s86, v2, v58
	v_add_u32_e32 v181, s0, v63
	s_add_i32 s0, 0, 0x12000
	v_lshl_add_u64 v[144:145], s[74:75], 0, v[2:3]
	v_lshlrev_b32_e32 v2, 12, v57
	s_add_u32 s54, s72, s54
	v_lshl_add_u32 v2, s83, 15, v2
	s_addc_u32 s55, s73, 0
	v_or_b32_e32 v2, v2, v58
	s_add_i32 s85, s85, s84
	s_lshl_b32 s72, s82, 1
	v_sub_f32_e32 v38, v38, v140
	v_sub_f32_e32 v39, v39, v140
	v_sub_f32_e32 v40, v40, v140
	v_sub_f32_e32 v41, v41, v140
	v_sub_f32_e32 v42, v42, v140
	v_sub_f32_e32 v43, v43, v140
	v_sub_f32_e32 v44, v44, v140
	v_sub_f32_e32 v36, v45, v140
	v_sub_f32_e32 v37, v46, v140
	v_sub_f32_e32 v45, v47, v140
	v_sub_f32_e32 v46, v48, v140
	v_sub_f32_e32 v47, v49, v140
	v_sub_f32_e32 v48, v50, v140
	v_sub_f32_e32 v49, v51, v140
	v_lshl_add_u64 v[146:147], s[54:55], 0, v[2:3]
	v_add3_u32 v2, s85, v59, v60
	s_and_b32 s72, s72, 0x80
	v_exp_f32_e32 v112, v38
	v_exp_f32_e32 v113, v39
	v_exp_f32_e32 v110, v40
	v_exp_f32_e32 v111, v41
	v_exp_f32_e32 v108, v42
	v_exp_f32_e32 v109, v43
	v_exp_f32_e32 v106, v44
	v_exp_f32_e32 v107, v36
	v_exp_f32_e32 v104, v37
	v_lshl_or_b32 v2, v2, 12, s72
	v_exp_f32_e32 v105, v45
	v_exp_f32_e32 v102, v46
	v_exp_f32_e32 v103, v47
	v_exp_f32_e32 v100, v48
	v_exp_f32_e32 v101, v49
	v_lshl_add_u32 v2, v164, 6, v2
	v_sub_f32_e32 v133, v23, v140
	v_sub_f32_e32 v160, v24, v140
	v_sub_f32_e32 v161, v25, v140
	v_sub_f32_e32 v158, v26, v140
	v_sub_f32_e32 v159, v27, v140
	v_sub_f32_e32 v156, v28, v140
	v_sub_f32_e32 v157, v29, v140
	v_sub_f32_e32 v154, v30, v140
	v_sub_f32_e32 v155, v31, v140
	v_sub_f32_e32 v152, v32, v140
	v_sub_f32_e32 v153, v33, v140
	v_sub_f32_e32 v150, v34, v140
	v_sub_f32_e32 v151, v35, v140
	v_add_u32_e32 v182, s34, v63
	v_add_u32_e32 v183, s0, v63
	v_add_u32_e32 v184, s53, v63
	v_cmp_gt_u32_e64 s[0:1], 32, v56
	v_or_b32_e32 v2, v2, v61
	v_mov_b64_e32 v[66:67], v[18:19]
	v_mov_b64_e32 v[50:51], v[18:19]
	v_mov_b64_e32 v[34:35], v[18:19]
	s_mov_b32 s81, 1
	v_lshl_add_u32 v166, v163, 2, s57
	v_lshl_add_u64 v[148:149], s[54:55], 0, v[2:3]
	v_mov_b32_e32 v2, 0
	v_mov_b64_e32 v[64:65], v[16:17]
	v_mov_b64_e32 v[62:63], v[14:15]
	v_mov_b64_e32 v[60:61], v[12:13]
	v_mov_b64_e32 v[58:59], v[10:11]
	v_mov_b64_e32 v[56:57], v[8:9]
	v_mov_b64_e32 v[54:55], v[6:7]
	v_mov_b64_e32 v[52:53], v[4:5]
	v_mov_b64_e32 v[48:49], v[16:17]
	v_mov_b64_e32 v[46:47], v[14:15]
	v_mov_b64_e32 v[44:45], v[12:13]
	v_mov_b64_e32 v[42:43], v[10:11]
	v_mov_b64_e32 v[40:41], v[8:9]
	v_mov_b64_e32 v[38:39], v[6:7]
	v_mov_b64_e32 v[36:37], v[4:5]
	v_mov_b64_e32 v[32:33], v[16:17]
	v_mov_b64_e32 v[30:31], v[14:15]
	v_mov_b64_e32 v[28:29], v[12:13]
	v_mov_b64_e32 v[26:27], v[10:11]
	v_mov_b64_e32 v[24:25], v[8:9]
	v_mov_b64_e32 v[22:23], v[6:7]
	v_mov_b64_e32 v[20:21], v[4:5]
	ds_read_b128 v[238:241], v171
	ds_read_b128 v[242:245], v170
	ds_read_b128 v[248:251], v169
	ds_read_b128 v[252:255], v168
	s_waitcnt lgkmcnt(0)
; template <int G> __device__ __forceinline__ void fin_gap(f32x16& P0, f32x16& P1, float (&sacc)[4], unsigned (&cv)[16], u32x4 (&pw)[4]) {
;   if constexpr (G < 16) { P1[G] = __builtin_amdgcn_exp2f(P1[G]); sacc[G & 3] += P0[G]; }
;   else { constexpr int r = 2 * (G - 16); sacc[r & 3] += P1[r]; sacc[(r + 1) & 3] += P1[r + 1]; }
;   if constexpr (G < 4) cv[G] = cvtpk_c(P0[2 * G], P0[2 * G + 1]);
;   else if constexpr (G >= 6 && G < 10) { constexpr int i = G - 2; cv[i] = cvtpk_c(P0[2 * i], P0[2 * i + 1]); }
;   else if constexpr (G >= 12 && G < 16) { constexpr int i = G - 4, j = i - 8; cv[i] = cvtpk_c(P1[2 * j], P1[2 * j + 1]); }
;   else if constexpr (G >= 18 && G < 22) { constexpr int i = G - 6, j = i - 8; cv[i] = cvtpk_c(P1[2 * j], P1[2 * j + 1]); }
;   if constexpr (G == 4 || G == 10 || G == 16 || G == 22) { constexpr int q = (G - 4) / 6; auto r0 = __builtin_amdgcn_permlane32_swap(cv[4 * q], cv[4 * q + 2], false, false); pw[q].x = r0[0]; pw[q].z = r0[1]; }
;   if constexpr (G == 5 || G == 11 || G == 17 || G == 23) { constexpr int q = (G - 5) / 6; auto r1 = __builtin_amdgcn_permlane32_swap(cv[4 * q + 1], cv[4 * q + 3], false, false); pw[q].y = r1[0]; pw[q].w = r1[1]; }
; }
.LBB0_754:
	ds_read_b128 v[70:73], v178 offset:57344
	ds_read_b128 v[74:77], v178 offset:61440
	s_waitcnt lgkmcnt(0)
	v_mfma_f32_32x32x16_bf16 v[84:99], v[70:73], v[126:129], 0
	ds_read_b128 v[134:137], v179 offset:57344
	ds_read_b128 v[186:189], v179 offset:61440
	v_exp_f32_e32 v210, v130
	v_add_f32_e32 v185, 0, v68
	v_cvt_pk_bf16_f32 v130, v68, v1
	v_mfma_f32_32x32x16_bf16 v[68:83], v[74:77], v[126:129], 0
	v_exp_f32_e32 v211, v131
	v_add_f32_e32 v1, 0, v1
	v_cvt_pk_bf16_f32 v131, v112, v113
	s_waitcnt lgkmcnt(0)
	v_mfma_f32_32x32x16_bf16 v[84:99], v[134:137], v[122:125], v[84:99]
	ds_read_b128 v[190:193], v177 offset:57344
	ds_read_b128 v[194:197], v177 offset:61440
	v_exp_f32_e32 v212, v132
	v_add_f32_e32 v202, 0, v112
	v_cvt_pk_bf16_f32 v132, v110, v111
	v_mfma_f32_32x32x16_bf16 v[68:83], v[186:189], v[122:125], v[68:83]
	v_exp_f32_e32 v213, v133
	v_add_f32_e32 v203, 0, v113
	v_cvt_pk_bf16_f32 v133, v108, v109
	s_waitcnt lgkmcnt(0)
	v_mfma_f32_32x32x16_bf16 v[84:99], v[190:193], v[118:121], v[84:99]
	ds_read_b128 v[134:137], v176 offset:57344
	ds_read_b128 v[198:201], v176 offset:61440
	v_add_f32_e32 v189, v110, v185
	v_permlane32_swap_b32_e32 v130, v132
	v_exp_f32_e32 v214, v160
	v_mfma_f32_32x32x16_bf16 v[68:83], v[194:197], v[118:121], v[68:83]
	v_add_f32_e32 v1, v111, v1
	v_permlane32_swap_b32_e32 v131, v133
	v_exp_f32_e32 v215, v161
	s_waitcnt lgkmcnt(0)
	v_mfma_f32_32x32x16_bf16 v[84:99], v[134:137], v[114:117], v[84:99]
	v_add_u32_e32 v185, v181, v172
	v_add_u32_e32 v186, v182, v172
	ds_read_b128 v[110:113], v185
	ds_read_b128 v[190:193], v186
	v_add_f32_e32 v217, v108, v202
	v_cvt_pk_bf16_f32 v108, v106, v107
	v_exp_f32_e32 v216, v158
	v_mfma_f32_32x32x16_bf16 v[68:83], v[198:201], v[114:117], v[68:83]
	v_add_f32_e32 v219, v109, v203
	v_cvt_pk_bf16_f32 v109, v104, v105
	v_exp_f32_e32 v218, v159
	s_waitcnt lgkmcnt(0)
	v_mfma_f32_32x32x16_bf16 v[84:99], v[110:113], v[238:241], v[84:99]
	v_add_u32_e32 v187, v181, v173
	v_add_u32_e32 v188, v182, v173
	ds_read_b128 v[134:137], v187
	ds_read_b128 v[158:161], v188
	v_cvt_pk_bf16_f32 v110, v102, v103
	v_exp_f32_e32 v220, v156
	v_add_f32_e32 v112, v106, v189
	v_mfma_f32_32x32x16_bf16 v[68:83], v[190:193], v[238:241], v[68:83]
	v_add_f32_e32 v1, v107, v1
	v_cvt_pk_bf16_f32 v111, v100, v101
	v_exp_f32_e32 v113, v157
	s_waitcnt lgkmcnt(0)
	v_mfma_f32_32x32x16_bf16 v[84:99], v[134:137], v[242:245], v[84:99]
	v_add_u32_e32 v189, v181, v174
	v_add_u32_e32 v190, v182, v174
	ds_read_b128 v[194:197], v189
	ds_read_b128 v[202:205], v190
	v_permlane32_swap_b32_e32 v108, v110
	v_exp_f32_e32 v221, v154
	v_add_f32_e32 v217, v104, v217
	v_mfma_f32_32x32x16_bf16 v[68:83], v[158:161], v[242:245], v[68:83]
	v_permlane32_swap_b32_e32 v109, v111
	v_exp_f32_e32 v222, v155
	v_add_f32_e32 v219, v105, v219
	s_waitcnt lgkmcnt(0)
	v_mfma_f32_32x32x16_bf16 v[84:99], v[194:197], v[248:251], v[84:99]
	v_add_u32_e32 v191, v181, v175
	v_add_u32_e32 v192, v182, v175
	ds_read_b128 v[104:107], v191
	ds_read_b128 v[134:137], v192
	v_add_f32_e32 v112, v102, v112
	v_cvt_pk_bf16_f32 v102, v210, v211
	v_exp_f32_e32 v223, v152
	v_mfma_f32_32x32x16_bf16 v[68:83], v[202:205], v[248:251], v[68:83]
	v_add_f32_e32 v1, v103, v1
	v_cvt_pk_bf16_f32 v103, v212, v213
	v_exp_f32_e32 v226, v153
	s_waitcnt lgkmcnt(0)
	v_mfma_f32_32x32x16_bf16 v[84:99], v[104:107], v[252:255], v[84:99]
	v_add_u32_e32 v193, v183, v172
	v_add_u32_e32 v194, v184, v172
	ds_read_b128 v[158:161], v193
	ds_read_b128 v[198:201], v194
	ds_read_b128 v[202:205], v171 offset:4096
	v_cvt_pk_bf16_f32 v104, v214, v215
	v_exp_f32_e32 v227, v150
	v_add_f32_e32 v100, v100, v217
	v_mfma_f32_32x32x16_bf16 v[68:83], v[134:137], v[252:255], v[68:83]
	v_cvt_pk_bf16_f32 v105, v216, v218
	v_exp_f32_e32 v106, v151
	v_add_f32_e32 v101, v101, v219
	s_waitcnt lgkmcnt(0)
	v_mfma_f32_32x32x16_bf16 v[84:99], v[158:161], v[202:205], v[84:99]
	v_add_u32_e32 v195, v183, v173
	v_add_u32_e32 v196, v184, v173
	ds_read_b128 v[134:137], v195
	ds_read_b128 v[150:153], v196
	ds_read_b128 v[154:157], v170 offset:4096
	v_add_f32_e32 v1, v211, v1
	v_permlane32_swap_b32_e32 v102, v104
	v_add_f32_e32 v107, v210, v112
	v_mfma_f32_32x32x16_bf16 v[68:83], v[198:201], v[202:205], v[68:83]
	v_permlane32_swap_b32_e32 v103, v105
	v_add_f32_e32 v100, v212, v100
	v_add_f32_e32 v101, v213, v101
	s_waitcnt lgkmcnt(0)
	v_mfma_f32_32x32x16_bf16 v[84:99], v[134:137], v[154:157], v[84:99]
	v_add_u32_e32 v197, v183, v174
	v_add_u32_e32 v198, v184, v174
	ds_read_b128 v[158:161], v197
	ds_read_b128 v[202:205], v198
	ds_read_b128 v[206:209], v169 offset:4096
	v_add_f32_e32 v1, v215, v1
	v_cvt_pk_bf16_f32 v134, v220, v113
	v_add_f32_e32 v107, v214, v107
	v_mfma_f32_32x32x16_bf16 v[68:83], v[150:153], v[154:157], v[68:83]
	v_cvt_pk_bf16_f32 v135, v221, v222
	v_add_f32_e32 v100, v216, v100
	v_add_f32_e32 v101, v218, v101
	s_waitcnt lgkmcnt(0)
	v_mfma_f32_32x32x16_bf16 v[84:99], v[158:161], v[206:209], v[84:99]
	v_add_u32_e32 v199, v183, v175
	v_add_u32_e32 v200, v184, v175
	ds_read_b128 v[150:153], v199
	ds_read_b128 v[154:157], v200
	ds_read_b128 v[210:213], v168 offset:4096
	v_add_f32_e32 v1, v113, v1
	v_cvt_pk_bf16_f32 v136, v223, v226
	v_add_f32_e32 v107, v220, v107
	v_mfma_f32_32x32x16_bf16 v[68:83], v[202:205], v[206:209], v[68:83]
	v_cvt_pk_bf16_f32 v137, v227, v106
	v_add_f32_e32 v100, v221, v100
	v_add_f32_e32 v101, v222, v101
	s_waitcnt lgkmcnt(0)
	v_mfma_f32_32x32x16_bf16 v[84:99], v[150:153], v[210:213], v[84:99]
	v_add_f32_e32 v1, v226, v1
	v_permlane32_swap_b32_e32 v134, v136
	v_add_f32_e32 v107, v223, v107
	v_mfma_f32_32x32x16_bf16 v[68:83], v[154:157], v[210:213], v[68:83]
	v_permlane32_swap_b32_e32 v135, v137
	v_add_f32_e32 v100, v227, v100
	v_add_f32_e32 v101, v106, v101
	v_add_f32_e32 v1, v107, v1
	v_add_f32_e32 v100, v100, v101
	v_add_f32_e32 v201, v1, v100
	v_mov_b32_e32 v202, v201
	s_nop 1
	v_permlane32_swap_b32_e32 v201, v202

; #define MX3(a, b, c) __builtin_fmaxf(__builtin_fmaxf((a), (b)), (c))
; template <int G> __device__ __forceinline__ void par_gap(f32x16& C0, f32x16& C1, float& ma, float& mb, float mn) {
;   if constexpr (G == 0) { ma = MX3(C0[0], C0[1], C1[0]); mb = MX3(C0[2], C0[3], C1[1]); ma = MX3(ma, C1[2], C1[3]); ma = MX3(ma, C0[4], C0[5]); }
;   else if constexpr (G == 1) { mb = MX3(mb, C0[6], C0[7]); ma = MX3(ma, C1[4], C1[5]); mb = MX3(mb, C1[6], C1[7]); ma = MX3(ma, C0[8], C0[9]); }
;   else if constexpr (G == 2) { mb = MX3(mb, C0[10], C0[11]); ma = MX3(ma, C1[8], C1[9]); mb = MX3(mb, C1[10], C1[11]); ma = MX3(ma, C0[12], C0[13]); }
;   else if constexpr (G == 3) { mb = MX3(mb, C0[14], C0[15]); ma = MX3(ma, C1[12], C1[13]); mb = MX3(mb, C1[14], C1[15]); }
;   else if constexpr (G == 4) { _Pragma("unroll") for (int r = 0; r < 8; ++r) C0[r] -= mn; }
;   else if constexpr (G == 5) { _Pragma("unroll") for (int r = 8; r < 16; ++r) C0[r] -= mn; }
;   else if constexpr (G == 6) { _Pragma("unroll") for (int r = 0; r < 8; ++r) C1[r] -= mn; }
;   else if constexpr (G == 7) { _Pragma("unroll") for (int r = 8; r < 16; ++r) C1[r] -= mn; }
;   else if constexpr (G >= 8 && G < 12) { _Pragma("unroll") for (int r = 4 * (G - 8); r < 4 * (G - 8) + 4; ++r) C0[r] = __builtin_amdgcn_exp2f(C0[r]); }
; }
.Lattn_back_a:
	s_waitcnt lgkmcnt(6)
	v_mfma_f32_32x32x16_bf16 v[52:67], v[102:105], v[154:157], v[52:67]
	ds_read_b64_tr_b16 v[150:151], v167 offset:9216
	ds_read_b64_tr_b16 v[152:153], v167 offset:11264
	v_sub_f32_e32 v246, v84, v140
	v_sub_f32_e32 v84, v85, v140
	v_sub_f32_e32 v85, v86, v140
	v_sub_f32_e32 v86, v87, v140
	s_waitcnt lgkmcnt(6)
	v_mfma_f32_32x32x16_bf16 v[52:67], v[134:137], v[158:161], v[52:67]
	ds_read_b64_tr_b16 v[154:155], v167 offset:13312
	ds_read_b64_tr_b16 v[156:157], v167 offset:15360
	v_sub_f32_e32 v87, v88, v140
	v_sub_f32_e32 v88, v89, v140
	v_sub_f32_e32 v89, v90, v140
	v_sub_f32_e32 v90, v91, v140
	s_waitcnt lgkmcnt(6)
	v_mfma_f32_32x32x16_bf16 v[36:51], v[130:133], v[204:207], v[36:51]
	ds_read_b64_tr_b16 v[158:159], v167 offset:1536
	ds_read_b64_tr_b16 v[160:161], v167 offset:3584
	v_sub_f32_e32 v91, v92, v140
	v_sub_f32_e32 v92, v93, v140
	v_sub_f32_e32 v93, v94, v140
	v_sub_f32_e32 v94, v95, v140
	s_waitcnt lgkmcnt(6)
	v_mfma_f32_32x32x16_bf16 v[36:51], v[108:111], v[208:211], v[36:51]
	ds_read_b64_tr_b16 v[204:205], v167 offset:5632
	ds_read_b64_tr_b16 v[206:207], v167 offset:7680
	v_sub_f32_e32 v95, v96, v140
	v_sub_f32_e32 v96, v97, v140
	v_sub_f32_e32 v97, v98, v140
	v_sub_f32_e32 v98, v99, v140
	s_waitcnt lgkmcnt(6)
	v_mfma_f32_32x32x16_bf16 v[36:51], v[102:105], v[150:153], v[36:51]
	ds_read_b64_tr_b16 v[208:209], v167 offset:9728
	ds_read_b64_tr_b16 v[210:211], v167 offset:11776
	v_sub_f32_e32 v99, v68, v140
	v_sub_f32_e32 v216, v76, v140
	v_sub_f32_e32 v217, v77, v140
	v_sub_f32_e32 v218, v78, v140
	s_waitcnt lgkmcnt(6)
	v_mfma_f32_32x32x16_bf16 v[36:51], v[134:137], v[154:157], v[36:51]
	ds_read_b64_tr_b16 v[150:151], v167 offset:13824
	ds_read_b64_tr_b16 v[152:153], v167 offset:15872
	v_sub_f32_e32 v219, v79, v140
	v_sub_f32_e32 v220, v80, v140
	v_sub_f32_e32 v221, v81, v140
	v_sub_f32_e32 v222, v82, v140
	s_waitcnt lgkmcnt(6)
	v_mfma_f32_32x32x16_bf16 v[20:35], v[130:133], v[158:161], v[20:35]
	v_sub_f32_e32 v223, v83, v140
	v_exp_f32_e32 v212, v95
	s_waitcnt lgkmcnt(4)
	v_mfma_f32_32x32x16_bf16 v[20:35], v[108:111], v[204:207], v[20:35]
	v_exp_f32_e32 v213, v96
	v_exp_f32_e32 v214, v97
	s_waitcnt lgkmcnt(2)
	v_mfma_f32_32x32x16_bf16 v[20:35], v[102:105], v[208:211], v[20:35]
	v_exp_f32_e32 v215, v98
	s_waitcnt lgkmcnt(0)
	v_mfma_f32_32x32x16_bf16 v[20:35], v[134:137], v[150:153], v[20:35]
	v_cmp_gt_f32_e32 vcc, 1.0, v203
	s_cbranch_vccz .LBB0_759
	s_and_saveexec_b64 s[54:55], s[0:1]
	ds_write_b32 v166, v203 offset:128
	s_or_b64 exec, exec, s[54:55]
	s_waitcnt lgkmcnt(0)
	v_add_u32_e32 v1, s57, v165
	ds_read_b128 v[100:103], v1 offset:224
	ds_read_b128 v[104:107], v1 offset:192
	ds_read_b128 v[108:111], v1 offset:160
	ds_read_b128 v[130:133], v1 offset:128
	s_waitcnt lgkmcnt(3)
	v_pk_mul_f32 v[16:17], v[16:17], v[100:101]
	s_waitcnt lgkmcnt(2)
	v_pk_mul_f32 v[12:13], v[12:13], v[104:105]
	s_waitcnt lgkmcnt(1)
	v_pk_mul_f32 v[8:9], v[8:9], v[108:109]
	v_pk_mul_f32 v[18:19], v[18:19], v[102:103]
	v_pk_mul_f32 v[14:15], v[14:15], v[106:107]
	v_pk_mul_f32 v[10:11], v[10:11], v[110:111]
	s_waitcnt lgkmcnt(0)
	v_pk_mul_f32 v[6:7], v[6:7], v[132:133]
	v_pk_mul_f32 v[4:5], v[4:5], v[130:131]
	v_pk_mul_f32 v[64:65], v[64:65], v[100:101]
	v_pk_mul_f32 v[60:61], v[60:61], v[104:105]
	v_pk_mul_f32 v[56:57], v[56:57], v[108:109]
	v_pk_mul_f32 v[66:67], v[66:67], v[102:103]
	v_pk_mul_f32 v[62:63], v[62:63], v[106:107]
	v_pk_mul_f32 v[58:59], v[58:59], v[110:111]
	v_pk_mul_f32 v[54:55], v[54:55], v[132:133]
	v_pk_mul_f32 v[52:53], v[52:53], v[130:131]
	v_pk_mul_f32 v[48:49], v[48:49], v[100:101]
	v_pk_mul_f32 v[44:45], v[44:45], v[104:105]
	v_pk_mul_f32 v[40:41], v[40:41], v[108:109]
	v_pk_mul_f32 v[50:51], v[50:51], v[102:103]
	v_pk_mul_f32 v[46:47], v[46:47], v[106:107]
	v_pk_mul_f32 v[42:43], v[42:43], v[110:111]
	v_pk_mul_f32 v[38:39], v[38:39], v[132:133]
	v_pk_mul_f32 v[36:37], v[36:37], v[130:131]
	v_pk_mul_f32 v[32:33], v[32:33], v[100:101]
	v_pk_mul_f32 v[28:29], v[28:29], v[104:105]
	v_pk_mul_f32 v[24:25], v[24:25], v[108:109]
	v_pk_mul_f32 v[34:35], v[34:35], v[102:103]
	v_pk_mul_f32 v[30:31], v[30:31], v[106:107]
	v_pk_mul_f32 v[26:27], v[26:27], v[110:111]
	v_pk_mul_f32 v[22:23], v[22:23], v[132:133]
	v_pk_mul_f32 v[20:21], v[20:21], v[130:131]
; #define SBAR() __builtin_amdgcn_sched_barrier(0)
; #define DMA_K(t, bf) do { if (ABL & 8) break; const char* kb_ = Kt + (size_t)(t) * KSTEP; LAS unsigned char* kd_ = Kl + (bf) * SHM_K + wid * 1024; \
;     glds16(kb_ + voffK, kd_); glds16(kb_ + 128 + voffK, kd_ + 8192); glds16(Pt + (size_t)(t) * PSTEP + voffP, kd_ + 16384); } while (0)
; #define DMA_V(t, bf) do { if (ABL & 8) break; const char* vb_ = Kt + 256 + (size_t)(t) * KSTEP; LAS unsigned char* vd_ = Vl + (bf) * SHM_V + wid * 1024; \
;     glds16(vb_ + voffV, vd_); glds16(vb_ + (size_t)32 * LDKV * 2 + voffV, vd_ + 8192); } while (0)
; #define END_STEP() do { if (!(ABL & 8)) { asm volatile("s_waitcnt vmcnt(0)" ::: "memory"); __syncthreads(); } } while (0)
; template <int ABL> __device__ __forceinline__ void attn_unit(int b, int h, int qb, const bf16_t* Q, const bf16_t* KV, const bf16_t* KPE, bf16_t* MG, float* ssqa, LAS unsigned char* L) {
;     ...
;     END_STEP(); DMA_K(j + 2, 1); DMA_V(j + 1, 0);
;     SBAR(); QK_TILE(Kl, pA0, pA1, pB0, pB1, alB, true);
.LBB0_759:
	v_lshl_add_u64 v[112:113], s[28:29], 0, v[146:147]
	s_mov_b64 s[54:55], 0x18fc0000
	s_mov_b32 m0, s78
	v_lshl_add_u64 v[100:101], v[112:113], 0, s[54:55]
	s_waitcnt vmcnt(0)
	s_barrier
	global_load_lds_dwordx4 v[100:101], off
	v_lshl_add_u64 v[100:101], v[112:113], 0, s[38:39]
	s_add_i32 m0, s78, 0x2000
	v_lshl_add_u64 v[136:137], s[28:29], 0, v[144:145]
	global_load_lds_dwordx4 v[100:101], off
	v_lshl_add_u64 v[100:101], v[136:137], 0, s[40:41]
	s_add_i32 m0, s78, 0x4000
	v_lshl_add_u64 v[134:135], s[28:29], 0, v[148:149]
	global_load_lds_dwordx4 v[100:101], off
	v_lshl_add_u64 v[100:101], v[134:135], 0, s[42:43]
	s_mov_b32 m0, s58
	global_load_lds_dwordx4 v[100:101], off
	v_lshl_add_u64 v[100:101], v[134:135], 0, s[44:45]
	s_mov_b32 m0, s77
	global_load_lds_dwordx4 v[100:101], off
	v_exp_f32_e32 v1, v246
	v_exp_f32_e32 v101, v84
	v_exp_f32_e32 v103, v85
	v_exp_f32_e32 v205, v89
	v_exp_f32_e32 v206, v90
	v_sub_f32_e32 v102, v70, v140
	v_sub_f32_e32 v204, v74, v140
	v_exp_f32_e32 v160, v88
	v_sub_f32_e32 v88, v69, v140
	v_sub_f32_e32 v158, v72, v140
	v_exp_f32_e32 v154, v86
	v_exp_f32_e32 v159, v87
	v_exp_f32_e32 v208, v91
	v_exp_f32_e32 v209, v92
	v_exp_f32_e32 v210, v93
	v_exp_f32_e32 v211, v94
	v_sub_f32_e32 v155, v71, v140
	v_sub_f32_e32 v161, v73, v140
	v_sub_f32_e32 v207, v75, v140
	ds_read_b128 v[68:71], v178 offset:32768
	ds_read_b128 v[84:87], v178 offset:36864
	s_waitcnt lgkmcnt(0)
	v_mfma_f32_32x32x16_bf16 v[68:83], v[68:71], v[126:129], 0
	ds_read_b128 v[104:107], v179 offset:32768
	ds_read_b128 v[108:111], v179 offset:36864
	v_cvt_pk_bf16_f32 v100, v1, v101
	v_exp_f32_e32 v226, v99
	v_add_f32_e32 v227, 0, v1
	v_exp_f32_e32 v1, v88
	v_mfma_f32_32x32x16_bf16 v[84:99], v[84:87], v[126:129], 0
	v_add_f32_e32 v228, 0, v101
	v_cvt_pk_bf16_f32 v101, v103, v154
	s_waitcnt lgkmcnt(0)
	v_mfma_f32_32x32x16_bf16 v[68:83], v[104:107], v[122:125], v[68:83]
	ds_read_b128 v[130:133], v177 offset:32768
	ds_read_b128 v[150:153], v177 offset:36864
	v_exp_f32_e32 v229, v102
	v_cvt_pk_bf16_f32 v102, v159, v160
	v_add_f32_e32 v230, 0, v103
	v_mfma_f32_32x32x16_bf16 v[84:99], v[108:111], v[122:125], v[84:99]
	v_add_f32_e32 v105, 0, v154
	v_cvt_pk_bf16_f32 v103, v205, v206
	v_exp_f32_e32 v231, v155
	s_waitcnt lgkmcnt(0)
	v_mfma_f32_32x32x16_bf16 v[68:83], v[130:133], v[118:121], v[68:83]
	ds_read_b128 v[106:109], v176 offset:32768
	ds_read_b128 v[154:157], v176 offset:36864
	v_permlane32_swap_b32_e32 v100, v102
	v_exp_f32_e32 v232, v158
	v_add_f32_e32 v227, v159, v227
	v_mfma_f32_32x32x16_bf16 v[84:99], v[150:153], v[118:121], v[84:99]
	v_permlane32_swap_b32_e32 v101, v103
	v_exp_f32_e32 v233, v161
	v_add_f32_e32 v228, v160, v228
	s_waitcnt lgkmcnt(0)
	v_mfma_f32_32x32x16_bf16 v[68:83], v[106:109], v[114:117], v[68:83]
	ds_read_b128 v[130:133], v178 offset:40960
	ds_read_b128 v[150:153], v178 offset:45056
	v_cvt_pk_bf16_f32 v104, v208, v209
	v_exp_f32_e32 v234, v204
	v_add_f32_e32 v230, v205, v230
	v_mfma_f32_32x32x16_bf16 v[84:99], v[154:157], v[114:117], v[84:99]
	v_add_f32_e32 v236, v206, v105
	v_cvt_pk_bf16_f32 v105, v210, v211
	v_exp_f32_e32 v235, v207
	s_waitcnt lgkmcnt(0)
	v_mfma_f32_32x32x16_bf16 v[68:83], v[130:133], v[238:241], v[68:83]
	ds_read_b128 v[108:111], v179 offset:40960
	ds_read_b128 v[154:157], v179 offset:45056
	v_cvt_pk_bf16_f32 v106, v212, v213
	v_exp_f32_e32 v216, v216
	v_add_f32_e32 v227, v208, v227
	v_mfma_f32_32x32x16_bf16 v[84:99], v[150:153], v[238:241], v[84:99]
	v_cvt_pk_bf16_f32 v107, v214, v215
	v_exp_f32_e32 v217, v217
	v_add_f32_e32 v228, v209, v228
	s_waitcnt lgkmcnt(0)
	v_mfma_f32_32x32x16_bf16 v[68:83], v[108:111], v[242:245], v[68:83]
	ds_read_b128 v[130:133], v177 offset:40960
	ds_read_b128 v[150:153], v177 offset:45056
	v_permlane32_swap_b32_e32 v104, v106
	v_exp_f32_e32 v218, v218
	v_add_f32_e32 v230, v210, v230
	v_mfma_f32_32x32x16_bf16 v[84:99], v[154:157], v[242:245], v[84:99]
	v_add_f32_e32 v111, v211, v236
	v_permlane32_swap_b32_e32 v105, v107
	v_exp_f32_e32 v219, v219
	s_waitcnt lgkmcnt(0)
	v_mfma_f32_32x32x16_bf16 v[68:83], v[130:133], v[248:251], v[68:83]
	ds_read_b128 v[154:157], v176 offset:40960
	ds_read_b128 v[204:207], v176 offset:45056
	v_cvt_pk_bf16_f32 v108, v226, v1
	v_exp_f32_e32 v220, v220
	v_add_f32_e32 v212, v212, v227
	v_mfma_f32_32x32x16_bf16 v[84:99], v[150:153], v[248:251], v[84:99]
	v_cvt_pk_bf16_f32 v109, v229, v231
	v_exp_f32_e32 v221, v221
	v_add_f32_e32 v213, v213, v228
	s_waitcnt lgkmcnt(0)
	v_mfma_f32_32x32x16_bf16 v[68:83], v[154:157], v[252:255], v[68:83]
	ds_read_b128 v[130:133], v178 offset:49152
	ds_read_b128 v[150:153], v178 offset:53248
	ds_read_b128 v[158:161], v171 offset:4096
	v_cvt_pk_bf16_f32 v110, v232, v233
	v_exp_f32_e32 v222, v222
	v_add_f32_e32 v214, v214, v230
	v_mfma_f32_32x32x16_bf16 v[84:99], v[204:207], v[252:255], v[84:99]
	v_add_f32_e32 v215, v215, v111
	v_cvt_pk_bf16_f32 v111, v234, v235
	v_exp_f32_e32 v223, v223
	s_waitcnt lgkmcnt(0)
	v_mfma_f32_32x32x16_bf16 v[68:83], v[130:133], v[158:161], v[68:83]
	ds_read_b128 v[154:157], v179 offset:49152
	ds_read_b128 v[204:207], v179 offset:53248
	ds_read_b128 v[208:211], v170 offset:4096
	v_add_f32_e32 v1, v1, v213
	v_permlane32_swap_b32_e32 v108, v110
	v_add_f32_e32 v226, v226, v212
	v_mfma_f32_32x32x16_bf16 v[84:99], v[150:153], v[158:161], v[84:99]
	v_add_f32_e32 v131, v229, v214
	v_add_f32_e32 v132, v231, v215
	v_permlane32_swap_b32_e32 v109, v111
	s_waitcnt lgkmcnt(0)
	v_mfma_f32_32x32x16_bf16 v[68:83], v[154:157], v[208:211], v[68:83]
	ds_read_b128 v[150:153], v177 offset:49152
	ds_read_b128 v[158:161], v177 offset:53248
	ds_read_b128 v[212:215], v169 offset:4096
	v_add_f32_e32 v133, v232, v226
	v_add_f32_e32 v1, v233, v1
	v_cvt_pk_bf16_f32 v130, v216, v217
	v_mfma_f32_32x32x16_bf16 v[84:99], v[204:207], v[208:211], v[84:99]
	v_add_f32_e32 v226, v234, v131
	v_cvt_pk_bf16_f32 v131, v218, v219
	v_add_f32_e32 v227, v235, v132
	s_waitcnt lgkmcnt(0)
	v_mfma_f32_32x32x16_bf16 v[68:83], v[150:153], v[212:215], v[68:83]
	ds_read_b128 v[154:157], v176 offset:49152
	ds_read_b128 v[204:207], v176 offset:53248
	ds_read_b128 v[208:211], v168 offset:4096
	v_add_f32_e32 v1, v217, v1
	v_cvt_pk_bf16_f32 v132, v220, v221
	v_add_f32_e32 v216, v216, v133
	v_mfma_f32_32x32x16_bf16 v[84:99], v[158:161], v[212:215], v[84:99]
	v_cvt_pk_bf16_f32 v133, v222, v223
	v_add_f32_e32 v150, v218, v226
	v_add_f32_e32 v151, v219, v227
	s_waitcnt lgkmcnt(0)
	v_mfma_f32_32x32x16_bf16 v[68:83], v[154:157], v[208:211], v[68:83]
	v_add_f32_e32 v1, v221, v1
	v_permlane32_swap_b32_e32 v130, v132
	v_add_f32_e32 v152, v220, v216
	v_mfma_f32_32x32x16_bf16 v[84:99], v[204:207], v[208:211], v[84:99]
	v_permlane32_swap_b32_e32 v131, v133
	v_add_f32_e32 v150, v222, v150
	v_add_f32_e32 v151, v223, v151
	v_add_f32_e32 v1, v152, v1
	v_add_f32_e32 v150, v150, v151
	v_add_f32_e32 v205, v1, v150
	v_mov_b32_e32 v206, v205
	s_nop 1
	v_permlane32_swap_b32_e32 v205, v206
; #define MX3(a, b, c) __builtin_fmaxf(__builtin_fmaxf((a), (b)), (c))
; template <int G> __device__ __forceinline__ void par_gap(f32x16& C0, f32x16& C1, float& ma, float& mb, float mn) {
;   if constexpr (G == 0) { ma = MX3(C0[0], C0[1], C1[0]); mb = MX3(C0[2], C0[3], C1[1]); ma = MX3(ma, C1[2], C1[3]); ma = MX3(ma, C0[4], C0[5]); }
;   else if constexpr (G == 1) { mb = MX3(mb, C0[6], C0[7]); ma = MX3(ma, C1[4], C1[5]); mb = MX3(mb, C1[6], C1[7]); ma = MX3(ma, C0[8], C0[9]); }
;   else if constexpr (G == 2) { mb = MX3(mb, C0[10], C0[11]); ma = MX3(ma, C1[8], C1[9]); mb = MX3(mb, C1[10], C1[11]); ma = MX3(ma, C0[12], C0[13]); }
;   else if constexpr (G == 3) { mb = MX3(mb, C0[14], C0[15]); ma = MX3(ma, C1[12], C1[13]); mb = MX3(mb, C1[14], C1[15]); }
;   else if constexpr (G == 4) { _Pragma("unroll") for (int r = 0; r < 8; ++r) C0[r] -= mn; }
;   else if constexpr (G == 5) { _Pragma("unroll") for (int r = 8; r < 16; ++r) C0[r] -= mn; }
;   else if constexpr (G == 6) { _Pragma("unroll") for (int r = 0; r < 8; ++r) C1[r] -= mn; }
;   else if constexpr (G == 7) { _Pragma("unroll") for (int r = 8; r < 16; ++r) C1[r] -= mn; }
;   else if constexpr (G >= 8 && G < 12) { _Pragma("unroll") for (int r = 4 * (G - 8); r < 4 * (G - 8) + 4; ++r) C0[r] = __builtin_amdgcn_exp2f(C0[r]); }
; }
.LBB0_760:
	ds_read_b64_tr_b16 v[150:151], v167 offset:16384
	ds_read_b64_tr_b16 v[152:153], v167 offset:18432
	ds_read_b64_tr_b16 v[154:155], v167 offset:20480
	ds_read_b64_tr_b16 v[156:157], v167 offset:22528
	ds_read_b64_tr_b16 v[158:159], v167 offset:24576
	ds_read_b64_tr_b16 v[160:161], v167 offset:26624
	ds_read_b64_tr_b16 v[208:209], v167 offset:28672
	ds_read_b64_tr_b16 v[210:211], v167 offset:30720
	v_max_f32_e32 v1, v69, v69
	v_max_f32_e32 v237, v68, v68
	v_max_f32_e32 v1, v237, v1
	v_max3_f32 v237, v70, v71, v85
	v_max3_f32 v1, v1, v84, v86
	v_max3_f32 v1, v1, v87, v72
	v_max3_f32 v237, v237, v74, v75
	v_max3_f32 v1, v1, v73, v88
	v_max3_f32 v237, v237, v90, v91
	s_waitcnt lgkmcnt(6)
	v_mfma_f32_32x32x16_bf16 v[4:19], v[100:103], v[150:153], v[4:19]
	ds_read_b64_tr_b16 v[212:213], v167 offset:16896
	ds_read_b64_tr_b16 v[214:215], v167 offset:18944
	v_max3_f32 v1, v1, v89, v76
	v_max3_f32 v237, v237, v78, v79
	v_max3_f32 v1, v1, v77, v92
	s_waitcnt lgkmcnt(6)
	v_mfma_f32_32x32x16_bf16 v[4:19], v[104:107], v[154:157], v[4:19]
	ds_read_b64_tr_b16 v[150:151], v167 offset:20992
	ds_read_b64_tr_b16 v[152:153], v167 offset:23040
	v_max3_f32 v237, v237, v94, v95
	v_max3_f32 v1, v1, v93, v80
	v_max3_f32 v237, v237, v82, v83
	s_waitcnt lgkmcnt(6)
	v_mfma_f32_32x32x16_bf16 v[4:19], v[108:111], v[158:161], v[4:19]
	ds_read_b64_tr_b16 v[154:155], v167 offset:25088
	ds_read_b64_tr_b16 v[156:157], v167 offset:27136
	v_max3_f32 v1, v1, v81, v96
	v_max3_f32 v237, v237, v98, v99
	v_max3_f32 v1, v1, v97, v237
	s_waitcnt lgkmcnt(6)
	v_mfma_f32_32x32x16_bf16 v[4:19], v[130:133], v[208:211], v[4:19]
	ds_read_b64_tr_b16 v[158:159], v167 offset:29184
	ds_read_b64_tr_b16 v[160:161], v167 offset:31232
	v_mov_b32_e32 v237, v1
	s_waitcnt lgkmcnt(6)
	v_mfma_f32_32x32x16_bf16 v[52:67], v[100:103], v[212:215], v[52:67]
	ds_read_b64_tr_b16 v[208:209], v167 offset:17408
	ds_read_b64_tr_b16 v[210:211], v167 offset:19456
	v_permlane32_swap_b32_e32 v1, v237
	v_max_f32_e32 v237, v237, v237
	v_max_f32_e32 v1, v1, v1
	v_max_f32_e32 v1, v1, v237
	s_waitcnt lgkmcnt(6)
	v_mfma_f32_32x32x16_bf16 v[52:67], v[104:107], v[150:153], v[52:67]
	ds_read_b64_tr_b16 v[212:213], v167 offset:21504
	ds_read_b64_tr_b16 v[214:215], v167 offset:23552
	v_sub_f32_e32 v237, v1, v140
	v_cmp_ge_f32_e32 vcc, s3, v237
	s_cmp_eq_u64 vcc, exec
	v_mov_b32_e32 v204, 1.0
	s_cbranch_scc0 .LBB0_769
.Lattn_back_b:
	s_waitcnt lgkmcnt(6)
	v_mfma_f32_32x32x16_bf16 v[52:67], v[108:111], v[154:157], v[52:67]
	ds_read_b64_tr_b16 v[150:151], v167 offset:25600
	ds_read_b64_tr_b16 v[152:153], v167 offset:27648
	v_sub_f32_e32 v246, v68, v140
	v_sub_f32_e32 v69, v69, v140
	v_sub_f32_e32 v70, v70, v140
	s_waitcnt lgkmcnt(6)
	v_mfma_f32_32x32x16_bf16 v[52:67], v[130:133], v[158:161], v[52:67]
	ds_read_b64_tr_b16 v[154:155], v167 offset:29696
	ds_read_b64_tr_b16 v[156:157], v167 offset:31744
	v_sub_f32_e32 v71, v71, v140
	v_sub_f32_e32 v72, v72, v140
	v_sub_f32_e32 v73, v73, v140
	s_waitcnt lgkmcnt(6)
	v_mfma_f32_32x32x16_bf16 v[36:51], v[100:103], v[208:211], v[36:51]
	ds_read_b64_tr_b16 v[158:159], v167 offset:17920
	ds_read_b64_tr_b16 v[160:161], v167 offset:19968
	v_sub_f32_e32 v74, v74, v140
	v_sub_f32_e32 v75, v75, v140
	v_sub_f32_e32 v76, v76, v140
	s_waitcnt lgkmcnt(6)
	v_mfma_f32_32x32x16_bf16 v[36:51], v[104:107], v[212:215], v[36:51]
	ds_read_b64_tr_b16 v[208:209], v167 offset:22016
	ds_read_b64_tr_b16 v[210:211], v167 offset:24064
	v_sub_f32_e32 v77, v77, v140
	v_sub_f32_e32 v78, v78, v140
	v_sub_f32_e32 v79, v79, v140
	s_waitcnt lgkmcnt(6)
	v_mfma_f32_32x32x16_bf16 v[36:51], v[108:111], v[150:153], v[36:51]
	ds_read_b64_tr_b16 v[212:213], v167 offset:26112
	ds_read_b64_tr_b16 v[214:215], v167 offset:28160
	v_sub_f32_e32 v80, v80, v140
	v_sub_f32_e32 v81, v81, v140
	v_sub_f32_e32 v82, v82, v140
	s_waitcnt lgkmcnt(6)
	v_mfma_f32_32x32x16_bf16 v[36:51], v[130:133], v[154:157], v[36:51]
	ds_read_b64_tr_b16 v[150:151], v167 offset:30208
	ds_read_b64_tr_b16 v[152:153], v167 offset:32256
	v_sub_f32_e32 v83, v83, v140
	v_exp_f32_e32 v68, v246
	s_waitcnt lgkmcnt(6)
	v_mfma_f32_32x32x16_bf16 v[20:35], v[100:103], v[158:161], v[20:35]
	s_waitcnt lgkmcnt(4)
	v_mfma_f32_32x32x16_bf16 v[20:35], v[104:107], v[208:211], v[20:35]
	s_waitcnt lgkmcnt(2)
	v_mfma_f32_32x32x16_bf16 v[20:35], v[108:111], v[212:215], v[20:35]
	s_waitcnt lgkmcnt(0)
	v_mfma_f32_32x32x16_bf16 v[20:35], v[130:133], v[150:153], v[20:35]
	v_cmp_gt_f32_e32 vcc, 1.0, v204
	s_cbranch_vccz .LBB0_764
	s_and_saveexec_b64 s[54:55], s[0:1]
	ds_write_b32 v166, v204 offset:128
	s_or_b64 exec, exec, s[54:55]
	s_waitcnt lgkmcnt(0)
	v_add_u32_e32 v1, s57, v165
	ds_read_b128 v[100:103], v1 offset:224
	ds_read_b128 v[104:107], v1 offset:192
	ds_read_b128 v[108:111], v1 offset:160
	ds_read_b128 v[130:133], v1 offset:128
	s_waitcnt lgkmcnt(3)
	v_pk_mul_f32 v[16:17], v[16:17], v[100:101]
	s_waitcnt lgkmcnt(2)
	v_pk_mul_f32 v[12:13], v[12:13], v[104:105]
	s_waitcnt lgkmcnt(1)
	v_pk_mul_f32 v[8:9], v[8:9], v[108:109]
	v_pk_mul_f32 v[18:19], v[18:19], v[102:103]
	v_pk_mul_f32 v[14:15], v[14:15], v[106:107]
	v_pk_mul_f32 v[10:11], v[10:11], v[110:111]
	s_waitcnt lgkmcnt(0)
	v_pk_mul_f32 v[6:7], v[6:7], v[132:133]
	v_pk_mul_f32 v[4:5], v[4:5], v[130:131]
	v_pk_mul_f32 v[64:65], v[64:65], v[100:101]
	v_pk_mul_f32 v[60:61], v[60:61], v[104:105]
	v_pk_mul_f32 v[56:57], v[56:57], v[108:109]
	v_pk_mul_f32 v[66:67], v[66:67], v[102:103]
	v_pk_mul_f32 v[62:63], v[62:63], v[106:107]
	v_pk_mul_f32 v[58:59], v[58:59], v[110:111]
	v_pk_mul_f32 v[54:55], v[54:55], v[132:133]
	v_pk_mul_f32 v[52:53], v[52:53], v[130:131]
	v_pk_mul_f32 v[48:49], v[48:49], v[100:101]
	v_pk_mul_f32 v[44:45], v[44:45], v[104:105]
	v_pk_mul_f32 v[40:41], v[40:41], v[108:109]
	v_pk_mul_f32 v[50:51], v[50:51], v[102:103]
	v_pk_mul_f32 v[46:47], v[46:47], v[106:107]
	v_pk_mul_f32 v[42:43], v[42:43], v[110:111]
	v_pk_mul_f32 v[38:39], v[38:39], v[132:133]
	v_pk_mul_f32 v[36:37], v[36:37], v[130:131]
	v_pk_mul_f32 v[32:33], v[32:33], v[100:101]
	v_pk_mul_f32 v[28:29], v[28:29], v[104:105]
	v_pk_mul_f32 v[24:25], v[24:25], v[108:109]
	v_pk_mul_f32 v[34:35], v[34:35], v[102:103]
	v_pk_mul_f32 v[30:31], v[30:31], v[106:107]
	v_pk_mul_f32 v[26:27], v[26:27], v[110:111]
	v_pk_mul_f32 v[22:23], v[22:23], v[132:133]
	v_pk_mul_f32 v[20:21], v[20:21], v[130:131]

.LBB0_769:
	v_max_f32_e32 v1, v1, v1
	v_max_f32_e32 v237, v140, v140
	v_max_f32_e32 v1, v237, v1
	v_sub_f32_e32 v140, v140, v1
	v_exp_f32_e32 v204, v140
	v_mov_b32_e32 v140, v1
	s_branch .Lattn_back_b
